# phase 4 unit order rotated: non-streaming units (prompt compression, sample pooling) first instead of as an HBM-idle last round; on top of the all-in stack
# speedup vs baseline: 1.0059x; 1.0059x over previous
.LBB0_1109:
	s_add_i32 s49, s45, 0xa00
	s_add_i32 s48, s45, 0xffffff60
	s_cmpk_lt_i32 s49, 0xaa0
	s_cselect_b32 s49, s49, s48
	s_mul_hi_i32 s6, s49, 0x66666667
	s_lshr_b32 s7, s6, 31
	s_ashr_i32 s26, s6, 1
	s_add_i32 s26, s26, s7
	s_mul_i32 s27, s26, -5
	s_add_i32 s27, s27, s49
	s_cmp_gt_i32 s27, 3
	s_mov_b64 s[6:7], -1
	s_cbranch_scc0 .LBB0_1169
	s_and_b32 s47, s26, 3
	s_lshl_b32 s29, s26, 5
	s_lshl_b32 s46, 2, s47
	s_and_b32 s28, s29, 0xffffff80
	s_lshl_b32 s6, s47, 17
	s_add_u32 s6, s31, s6
	s_addc_u32 s7, s33, 0
	s_cmpk_lt_i32 s28, 0x4000
	s_mov_b64 s[8:9], -1
	s_cbranch_scc0 .LBB0_1131
	s_and_b32 s10, s29, 0x780
	s_lshl_b32 s16, s47, 9
	s_add_i32 s11, s28, -15
	v_lshl_add_u64 v[2:3], v[124:125], 0, s[16:17]
	v_cmp_gt_i32_e32 vcc, s10, v105
	v_mov_b32_e32 v34, 0
	v_mov_b32_e32 v38, 0
	v_mov_b32_e32 v39, 0
	v_mov_b32_e32 v40, 0
	v_mov_b32_e32 v41, 0
	s_and_saveexec_b64 s[8:9], vcc
	s_cbranch_execz .LBB0_1113
	v_add_u32_e32 v4, s11, v1
	v_ashrrev_i32_e32 v5, 31, v4
	v_lshlrev_b64 v[4:5], 11, v[4:5]
	v_lshl_add_u64 v[4:5], v[2:3], 0, v[4:5]
	global_load_dwordx4 v[38:41], v[4:5], off
